# prompt attention K staging: per-chunk 1/rms by plain v_rsq_f32 + v_cndmask instead of an exec-masked branch with the denormal-safe rsqrt expansion (argument >= 1e-6)
# speedup vs baseline: 1.0085x; 1.0027x over previous
.LBB0_877:
	v_mov_b32_e32 v2, 1.0
	v_mov_b32_e32 v52, v240
	v_mov_b32_e32 v53, v241
	v_mov_b32_e32 v54, v243
	v_mov_b32_e32 v55, v252
	v_mov_b32_e32 v56, v248
	v_mov_b32_e32 v57, v249
	v_mov_b32_e32 v58, v250
	v_mov_b32_e32 v59, v251
	s_waitcnt vmcnt(4)
	v_and_b32_e32 v61, 0xffff0000, v116
	v_lshlrev_b32_e32 v60, 16, v116
	s_waitcnt lgkmcnt(2)
	v_pk_mul_f32 v[68:69], v[60:61], v[60:61]
	v_and_b32_e32 v63, 0xffff0000, v117
	v_lshlrev_b32_e32 v62, 16, v117
	v_pk_mul_f32 v[70:71], v[62:63], v[62:63]
	v_add_f32_e32 v68, v68, v69
	v_and_b32_e32 v65, 0xffff0000, v118
	v_lshlrev_b32_e32 v64, 16, v118
	v_add_f32_e32 v68, v70, v68
	v_pk_mul_f32 v[72:73], v[64:65], v[64:65]
	v_add_f32_e32 v68, v71, v68
	v_and_b32_e32 v67, 0xffff0000, v119
	v_lshlrev_b32_e32 v66, 16, v119
	v_add_f32_e32 v68, v72, v68
	v_pk_mul_f32 v[74:75], v[66:67], v[66:67]
	v_add_f32_e32 v68, v73, v68
	v_add_f32_e32 v68, v74, v68
	v_add_f32_e32 v68, v75, v68
	s_nop 1
	v_add_f32_dpp v68, v68, v68 quad_perm:[1,0,3,2] row_mask:0xf bank_mask:0xf
	s_nop 1
	v_add_f32_dpp v68, v68, v68 quad_perm:[2,3,0,1] row_mask:0xf bank_mask:0xf
	s_nop 1
	v_mov_b32_dpp v69, v68 row_half_mirror row_mask:0xf bank_mask:0xf
	v_add_f32_e32 v2, v68, v69
	v_fmamk_f32 v2, v2, 0x3c800000, v160
	v_rsq_f32_e32 v2, v2
	s_nop 0
	v_cndmask_b32_e64 v2, 1.0, v2, s[0:1]
	s_and_b32 s9, s28, 1
	s_lshl_b32 s4, s9, 15
	v_pk_mul_f32 v[60:61], v[2:3], v[60:61] op_sel_hi:[0,1]
	v_pk_mul_f32 v[62:63], v[2:3], v[62:63] op_sel_hi:[0,1]
	v_pk_mul_f32 v[64:65], v[2:3], v[64:65] op_sel_hi:[0,1]
	v_pk_mul_f32 v[66:67], v[2:3], v[66:67] op_sel_hi:[0,1]
	s_add_i32 s8, s4, 0
	s_waitcnt vmcnt(0)
	v_pk_mul_f32 v[60:61], v[56:57], v[60:61]
	v_pk_mul_f32 v[62:63], v[58:59], v[62:63]
	v_pk_mul_f32 v[64:65], v[52:53], v[64:65]
	v_pk_mul_f32 v[66:67], v[54:55], v[66:67]
	v_cvt_pk_bf16_f32 v60, v60, v61
	v_cvt_pk_bf16_f32 v61, v62, v63
	v_cvt_pk_bf16_f32 v62, v64, v65
	v_cvt_pk_bf16_f32 v63, v66, v67
	v_add3_u32 v2, s8, v201, v199
	ds_write_b128 v2, v[60:63]
	v_and_b32_e32 v61, 0xffff0000, v120
	v_lshlrev_b32_e32 v60, 16, v120
	s_waitcnt lgkmcnt(1)
	v_pk_mul_f32 v[68:69], v[60:61], v[60:61]
	v_and_b32_e32 v63, 0xffff0000, v121
	v_lshlrev_b32_e32 v62, 16, v121
	v_pk_mul_f32 v[70:71], v[62:63], v[62:63]
	v_add_f32_e32 v2, v68, v69
	v_and_b32_e32 v65, 0xffff0000, v122
	v_lshlrev_b32_e32 v64, 16, v122
	v_add_f32_e32 v2, v70, v2
	v_pk_mul_f32 v[72:73], v[64:65], v[64:65]
	v_add_f32_e32 v2, v71, v2
	v_and_b32_e32 v67, 0xffff0000, v123
	v_lshlrev_b32_e32 v66, 16, v123
	v_add_f32_e32 v2, v72, v2
	v_pk_mul_f32 v[74:75], v[66:67], v[66:67]
	v_add_f32_e32 v2, v73, v2
	v_add_f32_e32 v2, v74, v2
	v_add_f32_e32 v2, v75, v2
	s_nop 1
	v_add_f32_dpp v2, v2, v2 quad_perm:[1,0,3,2] row_mask:0xf bank_mask:0xf
	s_nop 1
	v_add_f32_dpp v69, v2, v2 quad_perm:[2,3,0,1] row_mask:0xf bank_mask:0xf
	s_nop 1
	v_mov_b32_dpp v70, v69 row_half_mirror row_mask:0xf bank_mask:0xf
	v_mov_b32_e32 v2, 1.0
	v_mov_b32_e32 v68, 1.0
	v_add_f32_e32 v68, v69, v70
	v_fmamk_f32 v68, v68, 0x3c800000, v160
	v_rsq_f32_e32 v68, v68
	s_nop 0
	v_cndmask_b32_e64 v68, 1.0, v68, s[0:1]
	v_pk_mul_f32 v[60:61], v[68:69], v[60:61] op_sel_hi:[0,1]
	v_pk_mul_f32 v[62:63], v[68:69], v[62:63] op_sel_hi:[0,1]
	v_pk_mul_f32 v[64:65], v[68:69], v[64:65] op_sel_hi:[0,1]
	v_pk_mul_f32 v[66:67], v[68:69], v[66:67] op_sel_hi:[0,1]
	v_pk_mul_f32 v[60:61], v[56:57], v[60:61]
	v_pk_mul_f32 v[62:63], v[58:59], v[62:63]
	v_pk_mul_f32 v[64:65], v[52:53], v[64:65]
	v_pk_mul_f32 v[66:67], v[54:55], v[66:67]
	v_cvt_pk_bf16_f32 v60, v60, v61
	v_cvt_pk_bf16_f32 v61, v62, v63
	v_cvt_pk_bf16_f32 v62, v64, v65
	v_cvt_pk_bf16_f32 v63, v66, v67
	v_add3_u32 v64, s8, v203, v202
	ds_write_b128 v64, v[60:63]
	v_and_b32_e32 v61, 0xffff0000, v124
	v_lshlrev_b32_e32 v60, 16, v124
	v_pk_mul_f32 v[68:69], v[60:61], v[60:61]
	v_and_b32_e32 v63, 0xffff0000, v125
	v_lshlrev_b32_e32 v62, 16, v125
	s_waitcnt lgkmcnt(1)
	v_pk_mul_f32 v[70:71], v[62:63], v[62:63]
	v_add_f32_e32 v68, v68, v69
	v_and_b32_e32 v65, 0xffff0000, v126
	v_lshlrev_b32_e32 v64, 16, v126
	v_add_f32_e32 v68, v70, v68
	v_pk_mul_f32 v[72:73], v[64:65], v[64:65]
	v_add_f32_e32 v68, v71, v68
	v_and_b32_e32 v67, 0xffff0000, v127
	v_lshlrev_b32_e32 v66, 16, v127
	v_add_f32_e32 v68, v72, v68
	v_pk_mul_f32 v[74:75], v[66:67], v[66:67]
	v_add_f32_e32 v68, v73, v68
	v_add_f32_e32 v68, v74, v68
	v_add_f32_e32 v68, v75, v68
	s_nop 1
	v_add_f32_dpp v68, v68, v68 quad_perm:[1,0,3,2] row_mask:0xf bank_mask:0xf
	s_nop 1
	v_add_f32_dpp v68, v68, v68 quad_perm:[2,3,0,1] row_mask:0xf bank_mask:0xf
	s_nop 1
	v_mov_b32_dpp v69, v68 row_half_mirror row_mask:0xf bank_mask:0xf
	v_add_f32_e32 v2, v68, v69
	v_fmamk_f32 v2, v2, 0x3c800000, v160
	v_rsq_f32_e32 v2, v2
	s_nop 0
	v_cndmask_b32_e64 v2, 1.0, v2, s[0:1]
	v_pk_mul_f32 v[60:61], v[2:3], v[60:61] op_sel_hi:[0,1]
	v_pk_mul_f32 v[62:63], v[2:3], v[62:63] op_sel_hi:[0,1]
	v_pk_mul_f32 v[64:65], v[2:3], v[64:65] op_sel_hi:[0,1]
	v_pk_mul_f32 v[66:67], v[2:3], v[66:67] op_sel_hi:[0,1]
	v_pk_mul_f32 v[60:61], v[56:57], v[60:61]
	v_pk_mul_f32 v[62:63], v[58:59], v[62:63]
	v_pk_mul_f32 v[64:65], v[52:53], v[64:65]
	v_pk_mul_f32 v[66:67], v[54:55], v[66:67]
	v_cvt_pk_bf16_f32 v60, v60, v61
	v_cvt_pk_bf16_f32 v61, v62, v63
	v_cvt_pk_bf16_f32 v62, v64, v65
	v_cvt_pk_bf16_f32 v63, v66, v67
	v_add3_u32 v2, s8, v205, v204
	ds_write_b128 v2, v[60:63]
	v_and_b32_e32 v61, 0xffff0000, v128
	v_lshlrev_b32_e32 v60, 16, v128
	s_waitcnt lgkmcnt(1)
	v_pk_mul_f32 v[68:69], v[60:61], v[60:61]
	v_and_b32_e32 v63, 0xffff0000, v129
	v_lshlrev_b32_e32 v62, 16, v129
	v_pk_mul_f32 v[70:71], v[62:63], v[62:63]
	v_add_f32_e32 v2, v68, v69
	v_and_b32_e32 v65, 0xffff0000, v130
	v_lshlrev_b32_e32 v64, 16, v130
	v_add_f32_e32 v2, v70, v2
	v_pk_mul_f32 v[72:73], v[64:65], v[64:65]
	v_add_f32_e32 v2, v71, v2
	v_and_b32_e32 v67, 0xffff0000, v131
	v_lshlrev_b32_e32 v66, 16, v131
	v_add_f32_e32 v2, v72, v2
	v_pk_mul_f32 v[74:75], v[66:67], v[66:67]
	v_add_f32_e32 v2, v73, v2
	v_add_f32_e32 v2, v74, v2
	v_add_f32_e32 v2, v75, v2
	s_nop 1
	v_add_f32_dpp v2, v2, v2 quad_perm:[1,0,3,2] row_mask:0xf bank_mask:0xf
	s_nop 1
	v_add_f32_dpp v68, v2, v2 quad_perm:[2,3,0,1] row_mask:0xf bank_mask:0xf
	s_nop 1
	v_mov_b32_dpp v69, v68 row_half_mirror row_mask:0xf bank_mask:0xf
	v_mov_b32_e32 v2, 1.0
	v_add_f32_e32 v2, v68, v69
	v_fmamk_f32 v2, v2, 0x3c800000, v160
	v_rsq_f32_e32 v2, v2
	s_nop 0
	v_cndmask_b32_e64 v2, 1.0, v2, s[0:1]
	v_pk_mul_f32 v[60:61], v[2:3], v[60:61] op_sel_hi:[0,1]
	v_pk_mul_f32 v[56:57], v[56:57], v[60:61]
	v_pk_mul_f32 v[60:61], v[2:3], v[62:63] op_sel_hi:[0,1]
	v_pk_mul_f32 v[58:59], v[58:59], v[60:61]
	v_pk_mul_f32 v[60:61], v[2:3], v[64:65] op_sel_hi:[0,1]
	v_pk_mul_f32 v[60:61], v[52:53], v[60:61]
	v_pk_mul_f32 v[52:53], v[2:3], v[66:67] op_sel_hi:[0,1]
	v_pk_mul_f32 v[62:63], v[54:55], v[52:53]
	s_mulk_i32 s9, 0x2800
	v_cvt_pk_bf16_f32 v52, v56, v57
	v_cvt_pk_bf16_f32 v53, v58, v59
	v_cvt_pk_bf16_f32 v54, v60, v61
	v_cvt_pk_bf16_f32 v55, v62, v63
	v_add3_u32 v2, s8, v219, v218
	ds_write_b128 v2, v[52:55]
	v_add_u32_e32 v2, s9, v220
	ds_write_b128 v2, v[132:135]
